# static softmax reference + per-CU start skew (XCD-major, 0-3/5 us) on GEMM phases 1,4,7,11 to de-synchronise epilogue store bursts
# speedup vs baseline: 1.0780x; 1.0063x over previous
.LBB0_219:
	s_cmp_lt_i32 s34, 2
	s_cselect_b64 s[4:5], -1, 0
	s_and_b64 s[10:11], s[4:5], s[2:3]
	s_andn2_b64 vcc, exec, s[10:11]
	s_cbranch_vccnz .LBB0_270
	s_and_b32 s98, s33, 7
	s_lshl_b32 s98, s98, 5
	s_lshr_b32 s99, s33, 3
	s_or_b32 s98, s98, s99
	s_lshr_b32 s98, s98, 2
.Lskew_p1:
	s_cmp_eq_u32 s98, 0
	s_cbranch_scc1 .Lskew_p1_done
	s_sleep 1
	s_sub_u32 s98, s98, 1
	s_branch .Lskew_p1
.Lskew_p1_done:
	s_cmp_gt_i32 s75, 31
	s_movk_i32 s2, 0x80
	s_cselect_b32 s50, s2, 0x82
	s_lshl_b32 s12, s50, 3
	s_and_b32 s2, s84, 0xffffffc0
	v_mbcnt_hi_u32_b32 v9, -1, v214
	v_or_b32_e32 v8, s2, v9
	s_cmp_lt_i32 s33, s12
	s_cselect_b64 s[2:3], -1, 0
	s_cmp_ge_i32 s33, s12
	s_nop 0
	v_readfirstlane_b32 s4, v8
	s_cbranch_scc1 .LBB0_222
	s_ashr_i32 s5, s33, 31
	s_lshr_b32 s5, s5, 29
	s_add_i32 s5, s33, s5
	s_ashr_i32 s6, s5, 3
	s_and_b32 s5, s5, -8
	s_sub_i32 s5, s33, s5
	s_lshr_b32 s7, s5, 31
	s_or_b32 s7, s50, s7
	s_mul_i32 s5, s7, s5
	s_add_i32 s5, s5, s6
	s_ashr_i32 s6, s5, 31
	s_lshr_b32 s6, s6, 26
	s_add_i32 s6, s5, s6
	s_ashr_i32 s7, s6, 6
	s_lshl_b32 s13, s7, 3
	s_sub_i32 s7, s50, s13
	s_waitcnt lgkmcnt(0)
	s_min_u32 s15, s7, 8
	s_andn2_b32 s6, s6, 63
	s_sub_i32 s5, s5, s6
	v_cvt_f32_ubyte0_e32 v1, s15
	v_cvt_f32_i32_e32 v0, s5
	v_rcp_iflag_f32_e32 v2, v1
	s_ashr_i32 s6, s5, 30
	s_or_b32 s14, s6, 1
	v_mul_f32_e32 v2, v0, v2
	v_trunc_f32_e32 v2, v2
	v_fma_f32 v0, -v2, v1, v0
	v_cvt_i32_f32_e32 v2, v2
	v_cmp_ge_f32_e64 s[6:7], |v0|, v1
	s_and_b64 s[6:7], s[6:7], exec
	s_cselect_b32 s6, s14, 0
	v_readfirstlane_b32 s7, v2
	s_add_i32 s6, s7, s6
	s_sext_i32_i8 s14, s6
	s_mul_i32 s6, s6, s15
	s_sub_i32 s5, s5, s6
	s_sext_i32_i8 s5, s5
	s_add_i32 s6, s13, s5

.LBB0_476:
	s_cmp_lt_i32 s34, 5
	s_cselect_b64 s[4:5], -1, 0
	s_and_b64 s[8:9], s[4:5], s[2:3]
	s_andn2_b64 vcc, exec, s[8:9]
	s_cbranch_vccnz .LBB0_523
	s_and_b32 s98, s33, 7
	s_lshl_b32 s98, s98, 5
	s_lshr_b32 s99, s33, 3
	s_or_b32 s98, s98, s99
	s_lshr_b32 s98, s98, 2

.Lskew_p4_done:
	s_and_b32 s10, s84, 0xffffffc0
	v_mbcnt_hi_u32_b32 v8, -1, v214
	s_cmpk_lt_i32 s33, 0xb00
	s_mov_b64 s[2:3], s[0:1]
	s_mov_b64 s[4:5], s[0:1]
	v_or_b32_e32 v10, s10, v8
	s_cselect_b64 s[6:7], -1, 0
	s_cmpk_gt_i32 s33, 0xaff
	s_waitcnt lgkmcnt(0)
	v_readfirstlane_b32 s22, v10
	s_cbranch_scc1 .LBB0_479
	s_ashr_i32 s10, s33, 31
	s_lshr_b32 s10, s10, 29
	s_add_i32 s10, s33, s10
	s_ashr_i32 s11, s10, 3
	s_and_b32 s10, s10, -8
	s_sub_i32 s10, s33, s10
	s_cmp_lt_i32 s10, 0
	s_movk_i32 s12, 0x161
	s_cselect_b32 s12, s12, 0x160
	s_mul_i32 s10, s10, s12
	s_add_i32 s10, s10, s11
	s_mul_hi_i32 s11, s10, 0x2e8ba2e9
	s_lshr_b32 s12, s11, 31
	s_ashr_i32 s11, s11, 5
	s_add_i32 s11, s11, s12
	s_lshl_b32 s12, s11, 3
	s_mulk_i32 s11, 0xb0
	s_sub_i32 s10, s10, s11
	s_sext_i32_i16 s11, s10
	s_bfe_u32 s11, s11, 0x3001c
	s_add_i32 s11, s10, s11
	s_sext_i32_i16 s13, s11
	s_and_b32 s11, s11, 0xfff8
	s_sub_i32 s10, s10, s11
	s_sext_i32_i16 s10, s10
	s_add_i32 s64, s12, s10
	s_ashr_i32 s62, s13, 3

.LBB0_695:
	s_cmp_lt_i32 s34, 8
	s_cselect_b64 s[4:5], -1, 0
	s_and_b64 s[12:13], s[4:5], s[2:3]
	s_andn2_b64 vcc, exec, s[12:13]
	s_cbranch_vccnz .LBB0_823
	s_and_b32 s98, s33, 7
	s_lshl_b32 s98, s98, 5
	s_lshr_b32 s99, s33, 3
	s_or_b32 s98, s98, s99
	s_lshr_b32 s98, s98, 2
.Lskew_p7:
	s_cmp_eq_u32 s98, 0
	s_cbranch_scc1 .Lskew_p7_done
	s_sleep 2
	s_sub_u32 s98, s98, 1
	s_branch .Lskew_p7
.Lskew_p7_done:
	s_and_b32 s6, s84, 0xffffffc0
	v_mbcnt_hi_u32_b32 v8, -1, v214
	v_or_b32_e32 v151, s6, v8
	s_cmpk_lt_i32 s33, 0x618
	s_mov_b64 s[2:3], s[0:1]
	s_mov_b64 s[16:17], s[0:1]
	v_mov_b32_e32 v9, v151
	s_cselect_b64 s[4:5], -1, 0
	s_cmpk_gt_i32 s33, 0x617
	s_waitcnt lgkmcnt(0)
	v_readfirstlane_b32 s22, v9
	s_cbranch_scc1 .LBB0_698
	s_ashr_i32 s6, s33, 31
	s_lshr_b32 s6, s6, 29
	s_add_i32 s6, s33, s6
	s_ashr_i32 s7, s6, 3
	s_and_b32 s6, s6, -8
	s_sub_i32 s6, s33, s6
	s_cmp_lt_i32 s6, 0
	s_movk_i32 s10, 0xc4
	s_cselect_b32 s10, s10, 0xc3
	s_mul_i32 s6, s6, s10
	s_add_i32 s6, s6, s7
	s_mul_hi_i32 s7, s6, 0x2aaaaaab
	s_lshr_b32 s10, s7, 31
	s_ashr_i32 s7, s7, 4
	s_add_i32 s7, s7, s10
	s_lshl_b32 s11, s7, 3
	s_sub_i32 s10, 0x82, s11
	s_mulk_i32 s7, 0x60
	s_min_u32 s14, s10, 8
	s_sub_i32 s15, s6, s7
	s_sext_i32_i8 s6, s15
	v_cvt_f32_ubyte0_e32 v1, s14
	v_cvt_f32_i32_e32 v0, s6
	v_rcp_iflag_f32_e32 v2, v1
	s_ashr_i32 s6, s6, 30
	s_or_b32 s10, s6, 1
	v_mul_f32_e32 v2, v0, v2
	v_trunc_f32_e32 v2, v2
	v_fma_f32 v0, -v2, v1, v0
	v_cvt_i32_f32_e32 v2, v2
	v_cmp_ge_f32_e64 s[6:7], |v0|, v1
	s_and_b64 s[6:7], s[6:7], exec
	s_cselect_b32 s6, s10, 0
	v_readfirstlane_b32 s7, v2
	s_add_i32 s6, s7, s6
	s_sext_i32_i8 s10, s6
	s_mul_i32 s6, s6, s14
	s_sub_i32 s6, s15, s6
	s_sext_i32_i8 s6, s6
	s_add_i32 s52, s11, s6

.LBB0_1197:
	s_cmp_lt_i32 s34, 12
	s_cselect_b64 s[4:5], -1, 0
	s_and_b64 s[10:11], s[4:5], s[2:3]
	s_andn2_b64 vcc, exec, s[10:11]
	s_cbranch_vccnz .LBB0_1244
	s_and_b32 s98, s33, 7
	s_lshl_b32 s98, s98, 5
	s_lshr_b32 s99, s33, 3
	s_or_b32 s98, s98, s99
	s_lshr_b32 s98, s98, 2

.Lskew_p11_done:
	s_and_b32 s12, s84, 0xffffffc0
	v_mbcnt_hi_u32_b32 v8, -1, v214
	s_cmpk_lt_i32 s33, 0xb00
	s_mov_b64 s[2:3], s[0:1]
	s_mov_b64 s[4:5], s[0:1]
	v_or_b32_e32 v10, s12, v8
	s_cselect_b64 s[6:7], -1, 0
	s_cmpk_gt_i32 s33, 0xaff
	s_waitcnt lgkmcnt(0)
	v_readfirstlane_b32 s22, v10
	s_cbranch_scc1 .LBB0_1200
	s_ashr_i32 s12, s33, 31
	s_lshr_b32 s12, s12, 29
	s_add_i32 s12, s33, s12
	s_ashr_i32 s13, s12, 3
	s_and_b32 s12, s12, -8
	s_sub_i32 s12, s33, s12
	s_cmp_lt_i32 s12, 0
	s_movk_i32 s14, 0x161
	s_cselect_b32 s14, s14, 0x160
	s_mul_i32 s12, s12, s14
	s_add_i32 s12, s12, s13
	s_mul_hi_i32 s13, s12, 0x2e8ba2e9
	s_lshr_b32 s14, s13, 31
	s_ashr_i32 s13, s13, 5
	s_add_i32 s13, s13, s14
	s_lshl_b32 s14, s13, 3
	s_mulk_i32 s13, 0xb0
	s_sub_i32 s12, s12, s13
	s_sext_i32_i16 s13, s12
	s_bfe_u32 s13, s13, 0x3001c
	s_add_i32 s13, s12, s13
	s_sext_i32_i16 s15, s13
	s_and_b32 s13, s13, 0xfff8
	s_sub_i32 s12, s12, s13
	s_sext_i32_i16 s12, s12
	s_add_i32 s58, s14, s12
	s_ashr_i32 s56, s15, 3
